# carry scan: global loads (not flat) and the full wait after the first 24 of 128 E loads moved behind the last load (all loads issued before any wait)
# speedup vs baseline: 1.0035x; 1.0000x over previous
.LBB0_547:
	v_bfe_u32 v1, v0, 6, 1
	v_ashrrev_i32_e32 v14, 11, v0
	v_lshl_add_u32 v2, v1, 5, v14
	v_ashrrev_i32_e32 v15, 31, v14
	v_mul_i32_i24_e32 v12, 33, v2
	v_lshlrev_b64 v[14:15], 10, v[14:15]
	v_lshrrev_b32_e32 v2, 1, v0
	v_ashrrev_i32_e32 v13, 31, v12
	v_and_or_b32 v14, v2, s12, v14
	v_lshlrev_b64 v[12:13], 9, v[12:13]
	v_lshlrev_b64 v[16:17], 10, v[14:15]
	v_lshl_add_u64 v[12:13], v[4:5], 0, v[12:13]
	v_lshl_add_u64 v[16:17], s[22:23], 0, v[16:17]
	v_lshlrev_b32_e32 v2, 9, v1
	v_add_co_u32_e32 v12, vcc, 0x4000, v12
	v_lshl_add_u64 v[16:17], v[16:17], 0, v[2:3]
	v_mad_i64_i32 v[14:15], s[10:11], v14, s13, v[8:9]
	v_lshlrev_b32_e32 v2, 8, v1
	v_addc_co_u32_e32 v13, vcc, 0, v13, vcc
	v_lshl_add_u64 v[142:143], v[16:17], 0, v[6:7]
	v_lshl_add_u64 v[14:15], v[14:15], 0, v[2:3]
	global_load_dwordx2 v[12:13], v[12:13], off
	v_lshl_add_u64 v[14:15], v[14:15], 0, v[10:11]
	v_add_co_u32_e32 v16, vcc, s14, v142
	v_lshl_add_u64 v[14:15], v[14:15], 0, s[8:9]
	s_nop 0
	v_addc_co_u32_e32 v17, vcc, 0, v143, vcc
	s_waitcnt lgkmcnt(0)
	global_load_dword v19, v[142:143], off offset:2048
	global_load_dword v18, v[142:143], off offset:2304
	global_load_dword v20, v[142:143], off offset:3072
	global_load_dword v21, v[142:143], off offset:3328
	global_load_dword v22, v[16:17], off
	global_load_dword v23, v[16:17], off offset:256
	global_load_dword v24, v[16:17], off offset:1024
	global_load_dword v25, v[16:17], off offset:1280
	global_load_dword v26, v[16:17], off offset:2048
	global_load_dword v27, v[16:17], off offset:2304
	global_load_dword v28, v[16:17], off offset:3072
	global_load_dword v29, v[16:17], off offset:3328
	v_add_co_u32_e32 v16, vcc, s15, v142
	v_and_b32_e32 v1, 64, v0
	s_nop 0
	v_addc_co_u32_e32 v17, vcc, 0, v143, vcc
	global_load_dword v30, v[16:17], off
	global_load_dword v31, v[16:17], off offset:256
	global_load_dword v32, v[16:17], off offset:1024
	global_load_dword v33, v[16:17], off offset:1280
	global_load_dword v34, v[16:17], off offset:2048
	global_load_dword v35, v[16:17], off offset:2304
	global_load_dword v36, v[16:17], off offset:3072
	global_load_dword v37, v[16:17], off offset:3328
	v_add_co_u32_e32 v16, vcc, s16, v142
	v_addc_co_u32_e32 v17, vcc, 0, v143, vcc
	global_load_dword v38, v[16:17], off
	global_load_dword v39, v[16:17], off offset:256
	global_load_dword v40, v[16:17], off offset:1024
	global_load_dword v41, v[16:17], off offset:1280
	global_load_dword v42, v[16:17], off offset:2048
	global_load_dword v43, v[16:17], off offset:2304
	global_load_dword v44, v[16:17], off offset:3072
	global_load_dword v45, v[16:17], off offset:3328
	v_add_co_u32_e32 v16, vcc, s7, v142
	s_nop 0
	v_addc_co_u32_e32 v17, vcc, 0, v143, vcc
	global_load_dword v46, v[16:17], off
	global_load_dword v47, v[16:17], off offset:256
	global_load_dword v48, v[16:17], off offset:1024
	global_load_dword v49, v[16:17], off offset:1280
	global_load_dword v50, v[16:17], off offset:2048
	global_load_dword v51, v[16:17], off offset:2304
	global_load_dword v52, v[16:17], off offset:3072
	global_load_dword v53, v[16:17], off offset:3328
	v_add_co_u32_e32 v16, vcc, s17, v142
	s_nop 1
	v_addc_co_u32_e32 v17, vcc, 0, v143, vcc
	global_load_dword v54, v[16:17], off
	global_load_dword v55, v[16:17], off offset:256
	global_load_dword v56, v[16:17], off offset:1024
	global_load_dword v57, v[16:17], off offset:1280
	global_load_dword v58, v[16:17], off offset:2048
	global_load_dword v59, v[16:17], off offset:2304
	global_load_dword v60, v[16:17], off offset:3072
	global_load_dword v61, v[16:17], off offset:3328
	v_add_co_u32_e32 v16, vcc, s33, v142
	s_nop 1
	v_addc_co_u32_e32 v17, vcc, 0, v143, vcc
	global_load_dword v62, v[16:17], off
	global_load_dword v63, v[16:17], off offset:256
	global_load_dword v64, v[16:17], off offset:1024
	global_load_dword v65, v[16:17], off offset:1280
	global_load_dword v66, v[16:17], off offset:2048
	global_load_dword v67, v[16:17], off offset:2304
	global_load_dword v68, v[16:17], off offset:3072
	global_load_dword v69, v[16:17], off offset:3328
	v_add_co_u32_e32 v16, vcc, s34, v142
	s_nop 1
	v_addc_co_u32_e32 v17, vcc, 0, v143, vcc
	global_load_dword v70, v[16:17], off
	global_load_dword v71, v[16:17], off offset:256
	global_load_dword v72, v[16:17], off offset:1024
	global_load_dword v73, v[16:17], off offset:1280
	global_load_dword v74, v[16:17], off offset:2048
	global_load_dword v75, v[16:17], off offset:2304
	global_load_dword v76, v[16:17], off offset:3072
	global_load_dword v77, v[16:17], off offset:3328
	v_add_co_u32_e32 v16, vcc, s35, v142
	s_nop 1
	v_addc_co_u32_e32 v17, vcc, 0, v143, vcc
	global_load_dword v78, v[16:17], off
	global_load_dword v79, v[16:17], off offset:256
	global_load_dword v80, v[16:17], off offset:1024
	global_load_dword v81, v[16:17], off offset:1280
	global_load_dword v82, v[16:17], off offset:2048
	global_load_dword v83, v[16:17], off offset:2304
	global_load_dword v86, v[16:17], off offset:3072
	global_load_dword v87, v[16:17], off offset:3328
	v_add_co_u32_e32 v16, vcc, s38, v142
	s_nop 1
	v_addc_co_u32_e32 v17, vcc, 0, v143, vcc
	global_load_dword v88, v[16:17], off
	global_load_dword v89, v[16:17], off offset:256
	global_load_dword v90, v[16:17], off offset:1024
	global_load_dword v91, v[16:17], off offset:1280
	global_load_dword v92, v[16:17], off offset:2048
	global_load_dword v93, v[16:17], off offset:2304
	global_load_dword v94, v[16:17], off offset:3072
	global_load_dword v95, v[16:17], off offset:3328
	v_add_co_u32_e32 v16, vcc, s39, v142
	s_nop 1
	v_addc_co_u32_e32 v17, vcc, 0, v143, vcc
	global_load_dword v96, v[16:17], off
	global_load_dword v97, v[16:17], off offset:256
	global_load_dword v98, v[16:17], off offset:1024
	global_load_dword v99, v[16:17], off offset:1280
	global_load_dword v100, v[16:17], off offset:2048
	global_load_dword v101, v[16:17], off offset:2304
	global_load_dword v102, v[16:17], off offset:3072
	global_load_dword v103, v[16:17], off offset:3328
	v_add_co_u32_e32 v16, vcc, s40, v142
	s_nop 1
	v_addc_co_u32_e32 v17, vcc, 0, v143, vcc
	global_load_dword v104, v[16:17], off
	global_load_dword v105, v[16:17], off offset:256
	global_load_dword v106, v[16:17], off offset:1024
	global_load_dword v107, v[16:17], off offset:1280
	global_load_dword v108, v[16:17], off offset:2048
	global_load_dword v109, v[16:17], off offset:2304
	global_load_dword v110, v[16:17], off offset:3072
	global_load_dword v111, v[16:17], off offset:3328
	v_add_co_u32_e32 v16, vcc, s41, v142
	s_nop 1
	v_addc_co_u32_e32 v17, vcc, 0, v143, vcc
	global_load_dword v112, v[16:17], off
	global_load_dword v113, v[16:17], off offset:256
	global_load_dword v114, v[16:17], off offset:1024
	global_load_dword v115, v[16:17], off offset:1280
	global_load_dword v116, v[16:17], off offset:2048
	global_load_dword v117, v[16:17], off offset:2304
	global_load_dword v118, v[16:17], off offset:3072
	global_load_dword v119, v[16:17], off offset:3328
	v_add_co_u32_e32 v16, vcc, s42, v142
	s_nop 1
	v_addc_co_u32_e32 v17, vcc, 0, v143, vcc
	global_load_dword v120, v[16:17], off
	global_load_dword v121, v[16:17], off offset:256
	global_load_dword v122, v[16:17], off offset:1024
	global_load_dword v123, v[16:17], off offset:1280
	global_load_dword v124, v[16:17], off offset:2048
	global_load_dword v125, v[16:17], off offset:2304
	global_load_dword v126, v[16:17], off offset:3072
	global_load_dword v127, v[16:17], off offset:3328
	v_add_co_u32_e32 v16, vcc, s43, v142
	s_nop 1
	v_addc_co_u32_e32 v17, vcc, 0, v143, vcc
	global_load_dword v132, v[16:17], off
	global_load_dword v133, v[16:17], off offset:256
	global_load_dword v130, v[16:17], off offset:1024
	global_load_dword v131, v[16:17], off offset:1280
	global_load_dword v134, v[16:17], off offset:2048
	global_load_dword v135, v[16:17], off offset:2304
	global_load_dword v128, v[16:17], off offset:3072
	global_load_dword v129, v[16:17], off offset:3328
	v_add_co_u32_e32 v16, vcc, 0xf000, v142
	s_nop 1
	v_addc_co_u32_e32 v17, vcc, 0, v143, vcc
	global_load_dword v84, v[142:143], off offset:1024
	global_load_dword v85, v[142:143], off offset:1280
	global_load_dword v140, v[16:17], off
	global_load_dword v141, v[16:17], off offset:256
	global_load_dword v139, v[16:17], off offset:1024
	global_load_dword v138, v[16:17], off offset:1280
	global_load_dword v136, v[16:17], off offset:2048
	global_load_dword v137, v[16:17], off offset:2304
	s_waitcnt vmcnt(63)
	v_pk_mul_f32 v[144:145], v[12:13], 0 op_sel_hi:[1,0]
	s_nop 0
	v_add_f32_e32 v2, v145, v144
	v_pk_mov_b32 v[16:17], v[12:13], v[12:13] op_sel:[1,0]
	v_cmp_ne_u32_e32 vcc, 0, v1
	v_sub_f32_e32 v1, v144, v145
	s_and_saveexec_b64 s[10:11], vcc
	s_xor_b64 s[10:11], exec, s[10:11]
	s_cbranch_execz .LBB0_549
	v_add_co_u32_e32 v142, vcc, 0xf000, v142
	s_nop 1
	v_addc_co_u32_e32 v143, vcc, 0, v143, vcc
	global_load_dword v150, v[142:143], off offset:3072
	global_load_dword v151, v[142:143], off offset:3328
	v_add_co_u32_e32 v142, vcc, s48, v14
	s_waitcnt vmcnt(0) lgkmcnt(0)
	v_add_f32_e32 v150, v1, v150
	v_addc_co_u32_e32 v143, vcc, 0, v15, vcc
	v_add_co_u32_e32 v144, vcc, s49, v14
	v_add_f32_e32 v2, v2, v151
	s_nop 0
	v_addc_co_u32_e32 v145, vcc, 0, v15, vcc
	v_add_co_u32_e32 v146, vcc, s50, v14
	v_cvt_pk_bf16_f32 v1, v150, s0
	s_nop 0
	v_addc_co_u32_e32 v147, vcc, 0, v15, vcc
	v_add_co_u32_e32 v148, vcc, 0x17000, v14
	v_cvt_pk_bf16_f32 v151, v2, s0
	s_nop 0
	v_addc_co_u32_e32 v149, vcc, 0, v15, vcc
	v_pk_mul_f32 v[152:153], v[16:17], v[2:3] op_sel_hi:[1,0]
	global_store_short v[148:149], v3, off offset:2560
	global_store_short v[148:149], v3, off offset:2688
	global_store_short v[148:149], v1, off offset:1024
	global_store_short v[148:149], v151, off offset:1152
	v_pk_fma_f32 v[148:149], v[12:13], v[150:151], v[152:153] neg_lo:[0,0,1] neg_hi:[0,0,1]
	v_pk_fma_f32 v[150:151], v[12:13], v[150:151], v[152:153] op_sel_hi:[1,0,1]
	s_nop 0
	v_mov_b32_e32 v149, v151
	v_pk_add_f32 v[136:137], v[136:137], v[148:149]
	s_nop 0
	v_cvt_pk_bf16_f32 v1, v136, s0
	v_cvt_pk_bf16_f32 v2, v137, s0
	v_pk_mul_f32 v[148:149], v[12:13], v[136:137]
	v_pk_mul_f32 v[136:137], v[16:17], v[136:137]
	global_store_short v[142:143], v1, off offset:3584
	global_store_short v[142:143], v2, off offset:3712
	v_sub_f32_e32 v1, v148, v149
	v_add_f32_e32 v136, v136, v137
	v_add_f32_e32 v2, v139, v1
	v_add_f32_e32 v136, v138, v136
	v_cvt_pk_bf16_f32 v1, v2, s0
	v_cvt_pk_bf16_f32 v138, v136, s0
	v_pk_mul_f32 v[136:137], v[16:17], v[136:137] op_sel_hi:[1,0]
	global_store_short v[142:143], v1, off offset:2048
	global_store_short v[142:143], v138, off offset:2176
	v_pk_fma_f32 v[138:139], v[12:13], v[2:3], v[136:137] neg_lo:[0,0,1] neg_hi:[0,0,1]
	v_pk_fma_f32 v[136:137], v[12:13], v[2:3], v[136:137] op_sel_hi:[1,0,1]
	s_nop 0
	v_mov_b32_e32 v139, v137
	v_pk_add_f32 v[136:137], v[140:141], v[138:139]
	s_nop 0
	v_cvt_pk_bf16_f32 v1, v136, s0
	v_cvt_pk_bf16_f32 v2, v137, s0
	v_pk_mul_f32 v[138:139], v[12:13], v[136:137]
	v_pk_mul_f32 v[136:137], v[16:17], v[136:137]
	global_store_short v[142:143], v1, off offset:512
	global_store_short v[142:143], v2, off offset:640
	v_sub_f32_e32 v1, v138, v139
	v_add_f32_e32 v136, v136, v137
	v_add_f32_e32 v2, v128, v1
	v_add_f32_e32 v128, v129, v136
	v_cvt_pk_bf16_f32 v1, v2, s0
	v_cvt_pk_bf16_f32 v136, v128, s0
	v_pk_mul_f32 v[128:129], v[16:17], v[128:129] op_sel_hi:[1,0]
	global_store_short v[144:145], v1, off offset:3072
	global_store_short v[144:145], v136, off offset:3200
	v_pk_fma_f32 v[136:137], v[12:13], v[2:3], v[128:129] neg_lo:[0,0,1] neg_hi:[0,0,1]
	v_pk_fma_f32 v[128:129], v[12:13], v[2:3], v[128:129] op_sel_hi:[1,0,1]
	s_nop 0
	v_mov_b32_e32 v137, v129
	v_pk_add_f32 v[128:129], v[134:135], v[136:137]
	s_nop 0
	v_cvt_pk_bf16_f32 v1, v128, s0
	v_cvt_pk_bf16_f32 v2, v129, s0
	v_pk_mul_f32 v[134:135], v[12:13], v[128:129]
	v_pk_mul_f32 v[128:129], v[16:17], v[128:129]
	global_store_short v[144:145], v1, off offset:1536
	global_store_short v[144:145], v2, off offset:1664
	v_sub_f32_e32 v1, v134, v135
	v_add_f32_e32 v128, v128, v129
	v_add_f32_e32 v2, v130, v1
	v_add_f32_e32 v128, v131, v128
	v_cvt_pk_bf16_f32 v1, v2, s0
	v_cvt_pk_bf16_f32 v130, v128, s0
	v_pk_mul_f32 v[128:129], v[16:17], v[128:129] op_sel_hi:[1,0]
	global_store_short v[144:145], v1, off
	global_store_short v[144:145], v130, off offset:128
	v_pk_fma_f32 v[130:131], v[12:13], v[2:3], v[128:129] neg_lo:[0,0,1] neg_hi:[0,0,1]
	v_pk_fma_f32 v[128:129], v[12:13], v[2:3], v[128:129] op_sel_hi:[1,0,1]
	s_nop 0
	v_mov_b32_e32 v131, v129
	v_pk_add_f32 v[128:129], v[132:133], v[130:131]
	s_nop 0
	v_cvt_pk_bf16_f32 v1, v128, s0
	v_cvt_pk_bf16_f32 v2, v129, s0
	v_pk_mul_f32 v[130:131], v[12:13], v[128:129]
	v_pk_mul_f32 v[128:129], v[16:17], v[128:129]
	global_store_short v[146:147], v1, off offset:2560
	global_store_short v[146:147], v2, off offset:2688
	v_sub_f32_e32 v1, v130, v131
	v_add_f32_e32 v128, v128, v129
	v_add_f32_e32 v2, v126, v1
	v_add_f32_e32 v126, v127, v128
	v_cvt_pk_bf16_f32 v1, v2, s0
	v_cvt_pk_bf16_f32 v128, v126, s0
	v_pk_mul_f32 v[126:127], v[16:17], v[126:127] op_sel_hi:[1,0]
	global_store_short v[146:147], v1, off offset:1024
	global_store_short v[146:147], v128, off offset:1152
	v_pk_fma_f32 v[128:129], v[12:13], v[2:3], v[126:127] neg_lo:[0,0,1] neg_hi:[0,0,1]
	v_pk_fma_f32 v[126:127], v[12:13], v[2:3], v[126:127] op_sel_hi:[1,0,1]
	s_nop 0
	v_mov_b32_e32 v129, v127
	v_pk_add_f32 v[124:125], v[124:125], v[128:129]
	v_add_co_u32_e32 v126, vcc, s51, v14
	v_cvt_pk_bf16_f32 v1, v124, s0
	s_nop 0
	v_addc_co_u32_e32 v127, vcc, 0, v15, vcc
	global_store_short v[126:127], v1, off offset:3584
	v_cvt_pk_bf16_f32 v1, v125, s0
	v_pk_mul_f32 v[128:129], v[12:13], v[124:125]
	global_store_short v[126:127], v1, off offset:3712
	v_sub_f32_e32 v1, v128, v129
	v_pk_mul_f32 v[124:125], v[16:17], v[124:125]
	v_add_f32_e32 v2, v122, v1
	v_add_f32_e32 v1, v124, v125
	v_add_f32_e32 v122, v123, v1
	v_cvt_pk_bf16_f32 v1, v2, s0
	global_store_short v[126:127], v1, off offset:2048
	v_cvt_pk_bf16_f32 v1, v122, s0
	v_pk_mul_f32 v[122:123], v[16:17], v[122:123] op_sel_hi:[1,0]
	global_store_short v[126:127], v1, off offset:2176
	v_pk_fma_f32 v[124:125], v[12:13], v[2:3], v[122:123] neg_lo:[0,0,1] neg_hi:[0,0,1]
	v_pk_fma_f32 v[122:123], v[12:13], v[2:3], v[122:123] op_sel_hi:[1,0,1]
	s_nop 0
	v_mov_b32_e32 v125, v123
	v_pk_add_f32 v[120:121], v[120:121], v[124:125]
	s_nop 0
	v_cvt_pk_bf16_f32 v1, v120, s0
	global_store_short v[126:127], v1, off offset:512
	v_cvt_pk_bf16_f32 v1, v121, s0
	v_pk_mul_f32 v[122:123], v[12:13], v[120:121]
	global_store_short v[126:127], v1, off offset:640
	v_sub_f32_e32 v1, v122, v123
	v_pk_mul_f32 v[120:121], v[16:17], v[120:121]
	v_add_f32_e32 v2, v118, v1
	v_add_f32_e32 v1, v120, v121
	v_add_co_u32_e32 v120, vcc, s54, v14
	v_add_f32_e32 v118, v119, v1
	v_cvt_pk_bf16_f32 v1, v2, s0
	v_addc_co_u32_e32 v121, vcc, 0, v15, vcc
	global_store_short v[120:121], v1, off offset:3072
	v_cvt_pk_bf16_f32 v1, v118, s0
	v_pk_mul_f32 v[118:119], v[16:17], v[118:119] op_sel_hi:[1,0]
	global_store_short v[120:121], v1, off offset:3200
	v_pk_fma_f32 v[122:123], v[12:13], v[2:3], v[118:119] neg_lo:[0,0,1] neg_hi:[0,0,1]
	v_pk_fma_f32 v[118:119], v[12:13], v[2:3], v[118:119] op_sel_hi:[1,0,1]
	s_nop 0
	v_mov_b32_e32 v123, v119
	v_pk_add_f32 v[116:117], v[116:117], v[122:123]
	s_nop 0
	v_cvt_pk_bf16_f32 v1, v116, s0
	global_store_short v[120:121], v1, off offset:1536
	v_cvt_pk_bf16_f32 v1, v117, s0
	v_pk_mul_f32 v[118:119], v[12:13], v[116:117]
	global_store_short v[120:121], v1, off offset:1664
	v_sub_f32_e32 v1, v118, v119
	v_pk_mul_f32 v[116:117], v[16:17], v[116:117]
	v_add_f32_e32 v2, v114, v1
	v_add_f32_e32 v1, v116, v117
	v_add_f32_e32 v114, v115, v1
	v_cvt_pk_bf16_f32 v1, v2, s0
	global_store_short v[120:121], v1, off
	v_cvt_pk_bf16_f32 v1, v114, s0
	v_pk_mul_f32 v[114:115], v[16:17], v[114:115] op_sel_hi:[1,0]
	global_store_short v[120:121], v1, off offset:128
	v_pk_fma_f32 v[116:117], v[12:13], v[2:3], v[114:115] neg_lo:[0,0,1] neg_hi:[0,0,1]
	v_pk_fma_f32 v[114:115], v[12:13], v[2:3], v[114:115] op_sel_hi:[1,0,1]
	s_nop 0
	v_mov_b32_e32 v117, v115
	v_pk_add_f32 v[112:113], v[112:113], v[116:117]
	v_add_co_u32_e32 v114, vcc, s55, v14
	v_cvt_pk_bf16_f32 v1, v112, s0
	s_nop 0
	v_addc_co_u32_e32 v115, vcc, 0, v15, vcc
	global_store_short v[114:115], v1, off offset:2560
	v_cvt_pk_bf16_f32 v1, v113, s0
	v_pk_mul_f32 v[116:117], v[12:13], v[112:113]
	global_store_short v[114:115], v1, off offset:2688
	v_sub_f32_e32 v1, v116, v117
	v_pk_mul_f32 v[112:113], v[16:17], v[112:113]
	v_add_f32_e32 v2, v110, v1
	v_add_f32_e32 v1, v112, v113
	v_add_f32_e32 v110, v111, v1
	v_cvt_pk_bf16_f32 v1, v2, s0
	global_store_short v[114:115], v1, off offset:1024
	v_cvt_pk_bf16_f32 v1, v110, s0
	v_pk_mul_f32 v[110:111], v[16:17], v[110:111] op_sel_hi:[1,0]
	global_store_short v[114:115], v1, off offset:1152
	v_pk_fma_f32 v[112:113], v[12:13], v[2:3], v[110:111] neg_lo:[0,0,1] neg_hi:[0,0,1]
	v_pk_fma_f32 v[110:111], v[12:13], v[2:3], v[110:111] op_sel_hi:[1,0,1]
	s_nop 0
	v_mov_b32_e32 v113, v111
	v_pk_add_f32 v[108:109], v[108:109], v[112:113]
	v_add_co_u32_e32 v110, vcc, s2, v14
	v_cvt_pk_bf16_f32 v1, v108, s0
	s_nop 0
	v_addc_co_u32_e32 v111, vcc, 0, v15, vcc
	global_store_short v[110:111], v1, off offset:3584
	v_cvt_pk_bf16_f32 v1, v109, s0
	v_pk_mul_f32 v[112:113], v[12:13], v[108:109]
	global_store_short v[110:111], v1, off offset:3712
	v_sub_f32_e32 v1, v112, v113
	v_pk_mul_f32 v[108:109], v[16:17], v[108:109]
	v_add_f32_e32 v2, v106, v1
	v_add_f32_e32 v1, v108, v109
	v_add_f32_e32 v106, v107, v1
	v_cvt_pk_bf16_f32 v1, v2, s0
	global_store_short v[110:111], v1, off offset:2048
	v_cvt_pk_bf16_f32 v1, v106, s0
	v_pk_mul_f32 v[106:107], v[16:17], v[106:107] op_sel_hi:[1,0]
	global_store_short v[110:111], v1, off offset:2176
	v_pk_fma_f32 v[108:109], v[12:13], v[2:3], v[106:107] neg_lo:[0,0,1] neg_hi:[0,0,1]
	v_pk_fma_f32 v[106:107], v[12:13], v[2:3], v[106:107] op_sel_hi:[1,0,1]
	s_nop 0
	v_mov_b32_e32 v109, v107
	v_pk_add_f32 v[104:105], v[104:105], v[108:109]
	s_nop 0
	v_cvt_pk_bf16_f32 v1, v104, s0
	global_store_short v[110:111], v1, off offset:512
	v_cvt_pk_bf16_f32 v1, v105, s0
	v_pk_mul_f32 v[106:107], v[12:13], v[104:105]
	global_store_short v[110:111], v1, off offset:640
	v_sub_f32_e32 v1, v106, v107
	v_pk_mul_f32 v[104:105], v[16:17], v[104:105]
	v_add_f32_e32 v2, v102, v1
	v_add_f32_e32 v1, v104, v105
	v_add_co_u32_e32 v104, vcc, s44, v14
	v_add_f32_e32 v102, v103, v1
	v_cvt_pk_bf16_f32 v1, v2, s0
	v_addc_co_u32_e32 v105, vcc, 0, v15, vcc
	global_store_short v[104:105], v1, off offset:3072
	v_cvt_pk_bf16_f32 v1, v102, s0
	v_pk_mul_f32 v[102:103], v[16:17], v[102:103] op_sel_hi:[1,0]
	global_store_short v[104:105], v1, off offset:3200
	v_pk_fma_f32 v[106:107], v[12:13], v[2:3], v[102:103] neg_lo:[0,0,1] neg_hi:[0,0,1]
	v_pk_fma_f32 v[102:103], v[12:13], v[2:3], v[102:103] op_sel_hi:[1,0,1]
	s_nop 0
	v_mov_b32_e32 v107, v103
	v_pk_add_f32 v[100:101], v[100:101], v[106:107]
	s_nop 0
	v_cvt_pk_bf16_f32 v1, v100, s0
	global_store_short v[104:105], v1, off offset:1536
	v_cvt_pk_bf16_f32 v1, v101, s0
	v_pk_mul_f32 v[102:103], v[12:13], v[100:101]
	global_store_short v[104:105], v1, off offset:1664
	v_sub_f32_e32 v1, v102, v103
	v_pk_mul_f32 v[100:101], v[16:17], v[100:101]
	v_add_f32_e32 v2, v98, v1
	v_add_f32_e32 v1, v100, v101
	v_add_f32_e32 v98, v99, v1
	v_cvt_pk_bf16_f32 v1, v2, s0
	global_store_short v[104:105], v1, off
	v_cvt_pk_bf16_f32 v1, v98, s0
	v_pk_mul_f32 v[98:99], v[16:17], v[98:99] op_sel_hi:[1,0]
	global_store_short v[104:105], v1, off offset:128
	v_pk_fma_f32 v[100:101], v[12:13], v[2:3], v[98:99] neg_lo:[0,0,1] neg_hi:[0,0,1]
	v_pk_fma_f32 v[98:99], v[12:13], v[2:3], v[98:99] op_sel_hi:[1,0,1]
	s_nop 0
	v_mov_b32_e32 v101, v99
	v_pk_add_f32 v[96:97], v[96:97], v[100:101]
	v_add_co_u32_e32 v98, vcc, s43, v14
	v_cvt_pk_bf16_f32 v1, v96, s0
	s_nop 0
	v_addc_co_u32_e32 v99, vcc, 0, v15, vcc
	global_store_short v[98:99], v1, off offset:2560
	v_cvt_pk_bf16_f32 v1, v97, s0
	v_pk_mul_f32 v[100:101], v[12:13], v[96:97]
	global_store_short v[98:99], v1, off offset:2688
	v_sub_f32_e32 v1, v100, v101
	v_pk_mul_f32 v[96:97], v[16:17], v[96:97]
	v_add_f32_e32 v2, v94, v1
	v_add_f32_e32 v1, v96, v97
	v_add_f32_e32 v94, v95, v1
	v_cvt_pk_bf16_f32 v1, v2, s0
	global_store_short v[98:99], v1, off offset:1024
	v_cvt_pk_bf16_f32 v1, v94, s0
	v_pk_mul_f32 v[94:95], v[16:17], v[94:95] op_sel_hi:[1,0]
	global_store_short v[98:99], v1, off offset:1152
	v_pk_fma_f32 v[96:97], v[12:13], v[2:3], v[94:95] neg_lo:[0,0,1] neg_hi:[0,0,1]
	v_pk_fma_f32 v[94:95], v[12:13], v[2:3], v[94:95] op_sel_hi:[1,0,1]
	s_nop 0
	v_mov_b32_e32 v97, v95
	v_pk_add_f32 v[92:93], v[92:93], v[96:97]
	v_add_co_u32_e32 v94, vcc, s42, v14
	v_cvt_pk_bf16_f32 v1, v92, s0
	s_nop 0
	v_addc_co_u32_e32 v95, vcc, 0, v15, vcc
	global_store_short v[94:95], v1, off offset:3584
	v_cvt_pk_bf16_f32 v1, v93, s0
	v_pk_mul_f32 v[96:97], v[12:13], v[92:93]
	global_store_short v[94:95], v1, off offset:3712
	v_sub_f32_e32 v1, v96, v97
	v_pk_mul_f32 v[92:93], v[16:17], v[92:93]
	v_add_f32_e32 v2, v90, v1
	v_add_f32_e32 v1, v92, v93
	v_add_f32_e32 v90, v91, v1
	v_cvt_pk_bf16_f32 v1, v2, s0
	global_store_short v[94:95], v1, off offset:2048
	v_cvt_pk_bf16_f32 v1, v90, s0
	v_pk_mul_f32 v[90:91], v[16:17], v[90:91] op_sel_hi:[1,0]
	global_store_short v[94:95], v1, off offset:2176
	v_pk_fma_f32 v[92:93], v[12:13], v[2:3], v[90:91] neg_lo:[0,0,1] neg_hi:[0,0,1]
	v_pk_fma_f32 v[90:91], v[12:13], v[2:3], v[90:91] op_sel_hi:[1,0,1]
	s_nop 0
	v_mov_b32_e32 v93, v91
	v_pk_add_f32 v[88:89], v[88:89], v[92:93]
	s_nop 0
	v_cvt_pk_bf16_f32 v1, v88, s0
	global_store_short v[94:95], v1, off offset:512
	v_cvt_pk_bf16_f32 v1, v89, s0
	v_pk_mul_f32 v[90:91], v[12:13], v[88:89]
	global_store_short v[94:95], v1, off offset:640
	v_sub_f32_e32 v1, v90, v91
	v_pk_mul_f32 v[88:89], v[16:17], v[88:89]
	v_add_f32_e32 v2, v86, v1
	v_add_f32_e32 v1, v88, v89
	v_add_co_u32_e32 v88, vcc, s41, v14
	v_add_f32_e32 v86, v87, v1
	v_cvt_pk_bf16_f32 v1, v2, s0
	v_addc_co_u32_e32 v89, vcc, 0, v15, vcc
	global_store_short v[88:89], v1, off offset:3072
	v_cvt_pk_bf16_f32 v1, v86, s0
	v_pk_mul_f32 v[86:87], v[16:17], v[86:87] op_sel_hi:[1,0]
	global_store_short v[88:89], v1, off offset:3200
	v_pk_fma_f32 v[90:91], v[12:13], v[2:3], v[86:87] neg_lo:[0,0,1] neg_hi:[0,0,1]
	v_pk_fma_f32 v[86:87], v[12:13], v[2:3], v[86:87] op_sel_hi:[1,0,1]
	s_nop 0
	v_mov_b32_e32 v91, v87
	v_pk_add_f32 v[82:83], v[82:83], v[90:91]
	s_nop 0
	v_cvt_pk_bf16_f32 v1, v82, s0
	global_store_short v[88:89], v1, off offset:1536
	v_cvt_pk_bf16_f32 v1, v83, s0
	v_pk_mul_f32 v[86:87], v[12:13], v[82:83]
	global_store_short v[88:89], v1, off offset:1664
	v_sub_f32_e32 v1, v86, v87
	v_pk_mul_f32 v[82:83], v[16:17], v[82:83]
	v_add_f32_e32 v2, v80, v1
	v_add_f32_e32 v1, v82, v83
	v_add_f32_e32 v80, v81, v1
	v_cvt_pk_bf16_f32 v1, v2, s0
	global_store_short v[88:89], v1, off
	v_cvt_pk_bf16_f32 v1, v80, s0
	v_pk_mul_f32 v[80:81], v[16:17], v[80:81] op_sel_hi:[1,0]
	global_store_short v[88:89], v1, off offset:128
	v_pk_fma_f32 v[82:83], v[12:13], v[2:3], v[80:81] neg_lo:[0,0,1] neg_hi:[0,0,1]
	v_pk_fma_f32 v[80:81], v[12:13], v[2:3], v[80:81] op_sel_hi:[1,0,1]
	s_nop 0
	v_mov_b32_e32 v83, v81
	v_pk_add_f32 v[78:79], v[78:79], v[82:83]
	v_add_co_u32_e32 v80, vcc, s40, v14
	v_cvt_pk_bf16_f32 v1, v78, s0
	s_nop 0
	v_addc_co_u32_e32 v81, vcc, 0, v15, vcc
	global_store_short v[80:81], v1, off offset:2560
	v_cvt_pk_bf16_f32 v1, v79, s0
	v_pk_mul_f32 v[82:83], v[12:13], v[78:79]
	global_store_short v[80:81], v1, off offset:2688
	v_sub_f32_e32 v1, v82, v83
	v_pk_mul_f32 v[78:79], v[16:17], v[78:79]
	v_add_f32_e32 v2, v76, v1
	v_add_f32_e32 v1, v78, v79
	v_add_f32_e32 v76, v77, v1
	v_cvt_pk_bf16_f32 v1, v2, s0
	global_store_short v[80:81], v1, off offset:1024
	v_cvt_pk_bf16_f32 v1, v76, s0
	v_pk_mul_f32 v[76:77], v[16:17], v[76:77] op_sel_hi:[1,0]
	global_store_short v[80:81], v1, off offset:1152
	v_pk_fma_f32 v[78:79], v[12:13], v[2:3], v[76:77] neg_lo:[0,0,1] neg_hi:[0,0,1]
	v_pk_fma_f32 v[76:77], v[12:13], v[2:3], v[76:77] op_sel_hi:[1,0,1]
	s_nop 0
	v_mov_b32_e32 v79, v77
	v_pk_add_f32 v[74:75], v[74:75], v[78:79]
	v_add_co_u32_e32 v76, vcc, s39, v14
	v_cvt_pk_bf16_f32 v1, v74, s0
	s_nop 0
	v_addc_co_u32_e32 v77, vcc, 0, v15, vcc
	global_store_short v[76:77], v1, off offset:3584
	v_cvt_pk_bf16_f32 v1, v75, s0
	v_pk_mul_f32 v[78:79], v[12:13], v[74:75]
	global_store_short v[76:77], v1, off offset:3712
	v_sub_f32_e32 v1, v78, v79
	v_pk_mul_f32 v[74:75], v[16:17], v[74:75]
	v_add_f32_e32 v2, v72, v1
	v_add_f32_e32 v1, v74, v75
	v_add_f32_e32 v72, v73, v1
	v_cvt_pk_bf16_f32 v1, v2, s0
	global_store_short v[76:77], v1, off offset:2048
	v_cvt_pk_bf16_f32 v1, v72, s0
	v_pk_mul_f32 v[72:73], v[16:17], v[72:73] op_sel_hi:[1,0]
	global_store_short v[76:77], v1, off offset:2176
	v_pk_fma_f32 v[74:75], v[12:13], v[2:3], v[72:73] neg_lo:[0,0,1] neg_hi:[0,0,1]
	v_pk_fma_f32 v[72:73], v[12:13], v[2:3], v[72:73] op_sel_hi:[1,0,1]
	s_nop 0
	v_mov_b32_e32 v75, v73
	v_pk_add_f32 v[70:71], v[70:71], v[74:75]
	s_nop 0
	v_cvt_pk_bf16_f32 v1, v70, s0
	global_store_short v[76:77], v1, off offset:512
	v_cvt_pk_bf16_f32 v1, v71, s0
	v_pk_mul_f32 v[72:73], v[12:13], v[70:71]
	global_store_short v[76:77], v1, off offset:640
	v_sub_f32_e32 v1, v72, v73
	v_pk_mul_f32 v[70:71], v[16:17], v[70:71]
	v_add_f32_e32 v2, v68, v1
	v_add_f32_e32 v1, v70, v71
	v_add_co_u32_e32 v70, vcc, s38, v14
	v_add_f32_e32 v68, v69, v1
	v_cvt_pk_bf16_f32 v1, v2, s0
	v_addc_co_u32_e32 v71, vcc, 0, v15, vcc
	global_store_short v[70:71], v1, off offset:3072
	v_cvt_pk_bf16_f32 v1, v68, s0
	v_pk_mul_f32 v[68:69], v[16:17], v[68:69] op_sel_hi:[1,0]
	global_store_short v[70:71], v1, off offset:3200
	v_pk_fma_f32 v[72:73], v[12:13], v[2:3], v[68:69] neg_lo:[0,0,1] neg_hi:[0,0,1]
	v_pk_fma_f32 v[68:69], v[12:13], v[2:3], v[68:69] op_sel_hi:[1,0,1]
	s_nop 0
	v_mov_b32_e32 v73, v69
	v_pk_add_f32 v[66:67], v[66:67], v[72:73]
	s_nop 0
	v_cvt_pk_bf16_f32 v1, v66, s0
	global_store_short v[70:71], v1, off offset:1536
	v_cvt_pk_bf16_f32 v1, v67, s0
	v_pk_mul_f32 v[68:69], v[12:13], v[66:67]
	global_store_short v[70:71], v1, off offset:1664
	v_sub_f32_e32 v1, v68, v69
	v_pk_mul_f32 v[66:67], v[16:17], v[66:67]
	v_add_f32_e32 v2, v64, v1
	v_add_f32_e32 v1, v66, v67
	v_add_f32_e32 v64, v65, v1
	v_cvt_pk_bf16_f32 v1, v2, s0
	global_store_short v[70:71], v1, off
	v_cvt_pk_bf16_f32 v1, v64, s0
	v_pk_mul_f32 v[64:65], v[16:17], v[64:65] op_sel_hi:[1,0]
	global_store_short v[70:71], v1, off offset:128
	v_pk_fma_f32 v[66:67], v[12:13], v[2:3], v[64:65] neg_lo:[0,0,1] neg_hi:[0,0,1]
	v_pk_fma_f32 v[64:65], v[12:13], v[2:3], v[64:65] op_sel_hi:[1,0,1]
	s_nop 0
	v_mov_b32_e32 v67, v65
	v_pk_add_f32 v[62:63], v[62:63], v[66:67]
	v_add_co_u32_e32 v64, vcc, s35, v14
	v_cvt_pk_bf16_f32 v1, v62, s0
	s_nop 0
	v_addc_co_u32_e32 v65, vcc, 0, v15, vcc
	global_store_short v[64:65], v1, off offset:2560
	v_cvt_pk_bf16_f32 v1, v63, s0
	v_pk_mul_f32 v[66:67], v[12:13], v[62:63]
	global_store_short v[64:65], v1, off offset:2688
	v_sub_f32_e32 v1, v66, v67
	v_pk_mul_f32 v[62:63], v[16:17], v[62:63]
	v_add_f32_e32 v2, v60, v1
	v_add_f32_e32 v1, v62, v63
	v_add_f32_e32 v60, v61, v1
	v_cvt_pk_bf16_f32 v1, v2, s0
	global_store_short v[64:65], v1, off offset:1024
	v_cvt_pk_bf16_f32 v1, v60, s0
	v_pk_mul_f32 v[60:61], v[16:17], v[60:61] op_sel_hi:[1,0]
	global_store_short v[64:65], v1, off offset:1152
	v_pk_fma_f32 v[62:63], v[12:13], v[2:3], v[60:61] neg_lo:[0,0,1] neg_hi:[0,0,1]
	v_pk_fma_f32 v[60:61], v[12:13], v[2:3], v[60:61] op_sel_hi:[1,0,1]
	s_nop 0
	v_mov_b32_e32 v63, v61
	v_pk_add_f32 v[58:59], v[58:59], v[62:63]
	v_add_co_u32_e32 v60, vcc, s34, v14
	v_cvt_pk_bf16_f32 v1, v58, s0
	s_nop 0
	v_addc_co_u32_e32 v61, vcc, 0, v15, vcc
	global_store_short v[60:61], v1, off offset:3584
	v_cvt_pk_bf16_f32 v1, v59, s0
	v_pk_mul_f32 v[62:63], v[12:13], v[58:59]
	global_store_short v[60:61], v1, off offset:3712
	v_sub_f32_e32 v1, v62, v63
	v_pk_mul_f32 v[58:59], v[16:17], v[58:59]
	v_add_f32_e32 v2, v56, v1
	v_add_f32_e32 v1, v58, v59
	v_add_f32_e32 v56, v57, v1
	v_cvt_pk_bf16_f32 v1, v2, s0
	global_store_short v[60:61], v1, off offset:2048
	v_cvt_pk_bf16_f32 v1, v56, s0
	v_pk_mul_f32 v[56:57], v[16:17], v[56:57] op_sel_hi:[1,0]
	global_store_short v[60:61], v1, off offset:2176
	v_pk_fma_f32 v[58:59], v[12:13], v[2:3], v[56:57] neg_lo:[0,0,1] neg_hi:[0,0,1]
	v_pk_fma_f32 v[56:57], v[12:13], v[2:3], v[56:57] op_sel_hi:[1,0,1]
	s_nop 0
	v_mov_b32_e32 v59, v57
	v_pk_add_f32 v[54:55], v[54:55], v[58:59]
	s_nop 0
	v_cvt_pk_bf16_f32 v1, v54, s0
	global_store_short v[60:61], v1, off offset:512
	v_cvt_pk_bf16_f32 v1, v55, s0
	v_pk_mul_f32 v[56:57], v[12:13], v[54:55]
	global_store_short v[60:61], v1, off offset:640
	v_sub_f32_e32 v1, v56, v57
	v_pk_mul_f32 v[54:55], v[16:17], v[54:55]
	v_add_f32_e32 v2, v52, v1
	v_add_f32_e32 v1, v54, v55
	v_add_co_u32_e32 v54, vcc, s33, v14
	v_add_f32_e32 v52, v53, v1
	v_cvt_pk_bf16_f32 v1, v2, s0
	v_addc_co_u32_e32 v55, vcc, 0, v15, vcc
	global_store_short v[54:55], v1, off offset:3072
	v_cvt_pk_bf16_f32 v1, v52, s0
	v_pk_mul_f32 v[52:53], v[16:17], v[52:53] op_sel_hi:[1,0]
	global_store_short v[54:55], v1, off offset:3200
	v_pk_fma_f32 v[56:57], v[12:13], v[2:3], v[52:53] neg_lo:[0,0,1] neg_hi:[0,0,1]
	v_pk_fma_f32 v[52:53], v[12:13], v[2:3], v[52:53] op_sel_hi:[1,0,1]
	s_nop 0
	v_mov_b32_e32 v57, v53
	v_pk_add_f32 v[50:51], v[50:51], v[56:57]
	s_nop 0
	v_cvt_pk_bf16_f32 v1, v50, s0
	global_store_short v[54:55], v1, off offset:1536
	v_cvt_pk_bf16_f32 v1, v51, s0
	v_pk_mul_f32 v[52:53], v[12:13], v[50:51]
	global_store_short v[54:55], v1, off offset:1664
	v_sub_f32_e32 v1, v52, v53
	v_pk_mul_f32 v[50:51], v[16:17], v[50:51]
	v_add_f32_e32 v2, v48, v1
	v_add_f32_e32 v1, v50, v51
	v_add_f32_e32 v48, v49, v1
	v_cvt_pk_bf16_f32 v1, v2, s0
	global_store_short v[54:55], v1, off
	v_cvt_pk_bf16_f32 v1, v48, s0
	v_pk_mul_f32 v[48:49], v[16:17], v[48:49] op_sel_hi:[1,0]
	global_store_short v[54:55], v1, off offset:128
	v_pk_fma_f32 v[50:51], v[12:13], v[2:3], v[48:49] neg_lo:[0,0,1] neg_hi:[0,0,1]
	v_pk_fma_f32 v[48:49], v[12:13], v[2:3], v[48:49] op_sel_hi:[1,0,1]
	s_nop 0
	v_mov_b32_e32 v51, v49
	v_pk_add_f32 v[46:47], v[46:47], v[50:51]
	v_add_co_u32_e32 v48, vcc, s17, v14
	v_cvt_pk_bf16_f32 v1, v46, s0
	s_nop 0
	v_addc_co_u32_e32 v49, vcc, 0, v15, vcc
	global_store_short v[48:49], v1, off offset:2560
	v_cvt_pk_bf16_f32 v1, v47, s0
	v_pk_mul_f32 v[50:51], v[12:13], v[46:47]
	global_store_short v[48:49], v1, off offset:2688
	v_sub_f32_e32 v1, v50, v51
	v_pk_mul_f32 v[46:47], v[16:17], v[46:47]
	v_add_f32_e32 v2, v44, v1
	v_add_f32_e32 v1, v46, v47
	v_add_f32_e32 v44, v45, v1
	v_cvt_pk_bf16_f32 v1, v2, s0
	global_store_short v[48:49], v1, off offset:1024
	v_cvt_pk_bf16_f32 v1, v44, s0
	v_pk_mul_f32 v[44:45], v[16:17], v[44:45] op_sel_hi:[1,0]
	global_store_short v[48:49], v1, off offset:1152
	v_pk_fma_f32 v[46:47], v[12:13], v[2:3], v[44:45] neg_lo:[0,0,1] neg_hi:[0,0,1]
	v_pk_fma_f32 v[44:45], v[12:13], v[2:3], v[44:45] op_sel_hi:[1,0,1]
	s_nop 0
	v_mov_b32_e32 v47, v45
	v_pk_add_f32 v[42:43], v[42:43], v[46:47]
	v_add_co_u32_e32 v44, vcc, s7, v14
	v_cvt_pk_bf16_f32 v1, v42, s0
	s_nop 0
	v_addc_co_u32_e32 v45, vcc, 0, v15, vcc
	global_store_short v[44:45], v1, off offset:3584
	v_cvt_pk_bf16_f32 v1, v43, s0
	v_pk_mul_f32 v[46:47], v[12:13], v[42:43]
	global_store_short v[44:45], v1, off offset:3712
	v_sub_f32_e32 v1, v46, v47
	v_pk_mul_f32 v[42:43], v[16:17], v[42:43]
	v_add_f32_e32 v2, v40, v1
	v_add_f32_e32 v1, v42, v43
	v_add_f32_e32 v40, v41, v1
	v_cvt_pk_bf16_f32 v1, v2, s0
	global_store_short v[44:45], v1, off offset:2048
	v_cvt_pk_bf16_f32 v1, v40, s0
	v_pk_mul_f32 v[40:41], v[16:17], v[40:41] op_sel_hi:[1,0]
	global_store_short v[44:45], v1, off offset:2176
	v_pk_fma_f32 v[42:43], v[12:13], v[2:3], v[40:41] neg_lo:[0,0,1] neg_hi:[0,0,1]
	v_pk_fma_f32 v[40:41], v[12:13], v[2:3], v[40:41] op_sel_hi:[1,0,1]
	s_nop 0
	v_mov_b32_e32 v43, v41
	v_pk_add_f32 v[38:39], v[38:39], v[42:43]
	s_nop 0
	v_cvt_pk_bf16_f32 v1, v38, s0
	global_store_short v[44:45], v1, off offset:512
	v_cvt_pk_bf16_f32 v1, v39, s0
	v_pk_mul_f32 v[40:41], v[12:13], v[38:39]
	global_store_short v[44:45], v1, off offset:640
	v_sub_f32_e32 v1, v40, v41
	v_pk_mul_f32 v[38:39], v[16:17], v[38:39]
	v_add_f32_e32 v2, v36, v1
	v_add_f32_e32 v1, v38, v39
	v_add_co_u32_e32 v38, vcc, s16, v14
	v_add_f32_e32 v36, v37, v1
	v_cvt_pk_bf16_f32 v1, v2, s0
	v_addc_co_u32_e32 v39, vcc, 0, v15, vcc
	global_store_short v[38:39], v1, off offset:3072
	v_cvt_pk_bf16_f32 v1, v36, s0
	v_pk_mul_f32 v[36:37], v[16:17], v[36:37] op_sel_hi:[1,0]
	global_store_short v[38:39], v1, off offset:3200
	v_pk_fma_f32 v[40:41], v[12:13], v[2:3], v[36:37] neg_lo:[0,0,1] neg_hi:[0,0,1]
	v_pk_fma_f32 v[36:37], v[12:13], v[2:3], v[36:37] op_sel_hi:[1,0,1]
	s_nop 0
	v_mov_b32_e32 v41, v37
	v_pk_add_f32 v[34:35], v[34:35], v[40:41]
	s_nop 0
	v_cvt_pk_bf16_f32 v1, v34, s0
	global_store_short v[38:39], v1, off offset:1536
	v_cvt_pk_bf16_f32 v1, v35, s0
	v_pk_mul_f32 v[36:37], v[12:13], v[34:35]
	global_store_short v[38:39], v1, off offset:1664
	v_sub_f32_e32 v1, v36, v37
	v_pk_mul_f32 v[34:35], v[16:17], v[34:35]
	v_add_f32_e32 v2, v32, v1
	v_add_f32_e32 v1, v34, v35
	v_add_f32_e32 v32, v33, v1
	v_cvt_pk_bf16_f32 v1, v2, s0
	global_store_short v[38:39], v1, off
	v_cvt_pk_bf16_f32 v1, v32, s0
	v_pk_mul_f32 v[32:33], v[16:17], v[32:33] op_sel_hi:[1,0]
	global_store_short v[38:39], v1, off offset:128
	v_pk_fma_f32 v[34:35], v[12:13], v[2:3], v[32:33] neg_lo:[0,0,1] neg_hi:[0,0,1]
	v_pk_fma_f32 v[32:33], v[12:13], v[2:3], v[32:33] op_sel_hi:[1,0,1]
	s_nop 0
	v_mov_b32_e32 v35, v33
	v_pk_add_f32 v[30:31], v[30:31], v[34:35]
	v_add_co_u32_e32 v32, vcc, s15, v14
	v_cvt_pk_bf16_f32 v1, v30, s0
	s_nop 0
	v_addc_co_u32_e32 v33, vcc, 0, v15, vcc
	global_store_short v[32:33], v1, off offset:2560
	v_cvt_pk_bf16_f32 v1, v31, s0
	v_pk_mul_f32 v[34:35], v[12:13], v[30:31]
	global_store_short v[32:33], v1, off offset:2688
	v_sub_f32_e32 v1, v34, v35
	v_pk_mul_f32 v[30:31], v[16:17], v[30:31]
	v_add_f32_e32 v2, v28, v1
	v_add_f32_e32 v1, v30, v31
	v_add_f32_e32 v28, v29, v1
	v_cvt_pk_bf16_f32 v1, v2, s0
	global_store_short v[32:33], v1, off offset:1024
	v_cvt_pk_bf16_f32 v1, v28, s0
	v_pk_mul_f32 v[28:29], v[16:17], v[28:29] op_sel_hi:[1,0]
	global_store_short v[32:33], v1, off offset:1152
	v_pk_fma_f32 v[30:31], v[12:13], v[2:3], v[28:29] neg_lo:[0,0,1] neg_hi:[0,0,1]
	v_pk_fma_f32 v[28:29], v[12:13], v[2:3], v[28:29] op_sel_hi:[1,0,1]
	s_nop 0
	v_mov_b32_e32 v31, v29
	v_pk_add_f32 v[26:27], v[26:27], v[30:31]
	v_add_co_u32_e32 v28, vcc, s14, v14
	v_cvt_pk_bf16_f32 v1, v26, s0
	s_nop 0
	v_addc_co_u32_e32 v29, vcc, 0, v15, vcc
	global_store_short v[28:29], v1, off offset:3584
	v_cvt_pk_bf16_f32 v1, v27, s0
	v_pk_mul_f32 v[30:31], v[12:13], v[26:27]
	global_store_short v[28:29], v1, off offset:3712
	v_sub_f32_e32 v1, v30, v31
	v_pk_mul_f32 v[26:27], v[16:17], v[26:27]
	v_add_f32_e32 v2, v24, v1
	v_add_f32_e32 v1, v26, v27
	v_add_f32_e32 v24, v25, v1
	v_cvt_pk_bf16_f32 v1, v2, s0
	global_store_short v[28:29], v1, off offset:2048
	v_cvt_pk_bf16_f32 v1, v24, s0
	v_pk_mul_f32 v[24:25], v[16:17], v[24:25] op_sel_hi:[1,0]
	global_store_short v[28:29], v1, off offset:2176
	v_pk_fma_f32 v[26:27], v[12:13], v[2:3], v[24:25] neg_lo:[0,0,1] neg_hi:[0,0,1]
	v_pk_fma_f32 v[24:25], v[12:13], v[2:3], v[24:25] op_sel_hi:[1,0,1]
	s_nop 0
	v_mov_b32_e32 v27, v25
	v_pk_add_f32 v[22:23], v[22:23], v[26:27]
	s_nop 0
	v_cvt_pk_bf16_f32 v1, v22, s0
	global_store_short v[28:29], v1, off offset:512
	v_cvt_pk_bf16_f32 v1, v23, s0
	v_pk_mul_f32 v[24:25], v[12:13], v[22:23]
	global_store_short v[28:29], v1, off offset:640
	v_sub_f32_e32 v1, v24, v25
	v_pk_mul_f32 v[22:23], v[16:17], v[22:23]
	v_add_f32_e32 v2, v20, v1
	v_add_f32_e32 v1, v22, v23
	v_add_f32_e32 v20, v21, v1
	v_cvt_pk_bf16_f32 v1, v2, s0
	global_store_short v[14:15], v1, off offset:3072
	v_cvt_pk_bf16_f32 v1, v20, s0
	v_pk_mul_f32 v[20:21], v[12:13], v[20:21] op_sel_hi:[1,0]
	global_store_short v[14:15], v1, off offset:3200
	v_pk_fma_f32 v[22:23], v[16:17], v[2:3], v[20:21] op_sel_hi:[1,0,1] neg_lo:[0,0,1] neg_hi:[0,0,1]
	v_pk_fma_f32 v[16:17], v[16:17], v[2:3], v[20:21] op_sel_hi:[1,0,1]
	s_nop 0
	v_mov_b32_e32 v17, v23
	v_pk_add_f32 v[16:17], v[18:19], v[16:17]
	s_nop 0
	v_cvt_pk_bf16_f32 v1, v17, s0
	global_store_short v[14:15], v1, off offset:1536
	v_cvt_pk_bf16_f32 v1, v16, s0
	global_store_short v[14:15], v1, off offset:1664
	v_mul_f32_e32 v1, v12, v17
	v_fma_f32 v1, -v13, v16, v1
	v_pk_mul_f32 v[12:13], v[12:13], v[16:17]
	v_add_f32_e32 v1, v84, v1
	v_add_f32_e32 v2, v13, v12
	v_add_f32_e32 v146, v85, v2
	v_cvt_pk_bf16_f32 v1, v1, s0
	global_store_short v[14:15], v1, off
